# EpiMla: each row block's two 8-byte stores merged into one 16-byte store (v_permlane16_swap of the packed bf16 pairs, column offset 16*bitrev2(fq))
# speedup vs baseline: 1.0213x; 1.0060x over previous
;     __device__ __forceinline__ void operator()(const f32x4 (&acc)[2][2][4][2], const Unit& u, int wr, int wc, int fr, int fq) const {
;     ...
;         for (int bj = 0; bj < 2; ++bj) {
;             const int cgp = u.pn * 8 + bj * 4 + wc;
;             const bool rope = (cgp < 12) && ((cgp % 3) == 2);
;             const int col0 = cgp * 32 + 4 * fq;
.LBB0_539:
	v_and_b32_e32 v226, 4, v138
	v_and_b32_e32 v227, 8, v138
	v_lshlrev_b32_e32 v226, 3, v226
	v_lshl_or_b32 v226, v227, 1, v226
	v_mov_b32_e32 v227, 0
	s_lshl_b32 s75, s17, 3
	s_or_b32 s18, s75, s58
	s_cmp_lt_i32 s18, 12
	s_cselect_b64 s[10:11], -1, 0
	s_cmp_gt_i32 s18, 11
	s_cselect_b64 s[4:5], -1, 0
	s_mov_b64 s[12:13], -1
	s_and_b64 vcc, exec, s[10:11]
	s_cbranch_vccnz .LBB0_541
	s_mul_hi_u32 s12, s18, 0xaaaaaaab
	s_lshr_b32 s12, s12, 1
	s_mul_i32 s12, s12, 3
	s_sub_i32 s19, s18, s12
	s_mov_b64 s[12:13], 0

; __device__ __forceinline__ u32x2 pack4(f32x4 v) { u32x2 w; w.x = pk2(v[0], v[1]); w.y = pk2(v[2], v[3]); return w; }
;     __device__ __forceinline__ void operator()(const f32x4 (&acc)[2][2][4][2], const Unit& u, int wr, int wc, int fr, int fq) const {
;     ...
;                     if (cgp < 12) { v0 = v0 * qs; v1 = v1 * qs; }
;                     const int bq = row >> 12, sq = row & (SEQ - 1);
;                     bf16_t* rowp;
;                     if (cgp < 12) rowp = O + ((size_t)(bq * 4 + cgp / 3) * SEQ + sq) * 96 + (cgp % 3) * 32 + 4 * fq;
;                     else if (cgp < 20) rowp = O + (size_t)T * 384 + ((size_t)(bq * 4 + (cgp - 12) / 2) * SEQ + sq) * 64 + ((cgp - 12) & 1) * 32 + 4 * fq;
;                     else rowp = O + (size_t)T * 640 + ((size_t)(bq * 4 + (cgp - 20) / 2) * SEQ + sq) * 64 + ((cgp - 20) & 1) * 32 + 4 * fq;
;                     if (cgp < 28) { *(u32x2*)(rowp) = pack4(v0); *(u32x2*)(rowp + 16) = pack4(v1); }
.LBB0_553:
	s_cmp_lt_i32 s18, 28
	s_cselect_b64 s[46:47], -1, 0
	s_cmp_gt_i32 s18, 27
	v_lshlrev_b32_e32 v112, 1, v138
	s_cbranch_scc1 .LBB0_555
	v_pk_mul_f32 v[154:155], v[128:129], s[76:77] op_sel_hi:[1,0]
	v_pk_mul_f32 v[156:157], v[126:127], s[76:77] op_sel_hi:[1,0]
	v_pk_mul_f32 v[158:159], v[124:125], s[76:77] op_sel_hi:[1,0]
	v_pk_mul_f32 v[160:161], v[122:123], s[76:77] op_sel_hi:[1,0]
	v_cndmask_b32_e64 v159, v125, v159, s[10:11]
	v_cndmask_b32_e64 v158, v124, v158, s[10:11]
	v_cndmask_b32_e64 v125, v129, v155, s[10:11]
	v_cndmask_b32_e64 v128, v128, v154, s[10:11]
	v_cndmask_b32_e64 v124, v127, v157, s[10:11]
	v_cndmask_b32_e64 v126, v126, v156, s[10:11]
	v_cndmask_b32_e64 v161, v123, v161, s[10:11]
	v_cndmask_b32_e64 v160, v122, v160, s[10:11]
	v_lshl_add_u64 v[122:123], v[148:149], 0, v[226:227]
	v_cvt_pk_bf16_f32 v228, v126, v124
	v_cvt_pk_bf16_f32 v229, v128, v125
	v_cvt_pk_bf16_f32 v230, v160, v161
	v_cvt_pk_bf16_f32 v231, v158, v159
	s_nop 1
	v_permlane16_swap_b32_e32 v228, v230
	v_permlane16_swap_b32_e32 v229, v231
	global_store_dwordx4 v[122:123], v[228:231], off
	s_nop 1

; __device__ __forceinline__ u32x2 pack4(f32x4 v) { u32x2 w; w.x = pk2(v[0], v[1]); w.y = pk2(v[2], v[3]); return w; }
;     __device__ __forceinline__ void operator()(const f32x4 (&acc)[2][2][4][2], const Unit& u, int wr, int wc, int fr, int fq) const {
;     ...
;                     if (cgp < 12) { v0 = v0 * qs; v1 = v1 * qs; }
;                     const int bq = row >> 12, sq = row & (SEQ - 1);
;                     bf16_t* rowp;
;                     if (cgp < 12) rowp = O + ((size_t)(bq * 4 + cgp / 3) * SEQ + sq) * 96 + (cgp % 3) * 32 + 4 * fq;
;                     else if (cgp < 20) rowp = O + (size_t)T * 384 + ((size_t)(bq * 4 + (cgp - 12) / 2) * SEQ + sq) * 64 + ((cgp - 12) & 1) * 32 + 4 * fq;
;                     else rowp = O + (size_t)T * 640 + ((size_t)(bq * 4 + (cgp - 20) / 2) * SEQ + sq) * 64 + ((cgp - 20) & 1) * 32 + 4 * fq;
;                     if (cgp < 28) { *(u32x2*)(rowp) = pack4(v0); *(u32x2*)(rowp + 16) = pack4(v1); }
.LBB0_595:
	v_pk_mul_f32 v[78:79], v[70:71], s[76:77] op_sel_hi:[1,0]
	v_pk_mul_f32 v[82:83], v[68:69], s[76:77] op_sel_hi:[1,0]
	v_pk_mul_f32 v[86:87], v[66:67], s[76:77] op_sel_hi:[1,0]
	v_pk_mul_f32 v[90:91], v[64:65], s[76:77] op_sel_hi:[1,0]
	v_cndmask_b32_e64 v87, v67, v87, s[10:11]
	v_cndmask_b32_e64 v86, v66, v86, s[10:11]
	v_cndmask_b32_e64 v67, v71, v79, s[10:11]
	v_cndmask_b32_e64 v70, v70, v78, s[10:11]
	v_cndmask_b32_e64 v66, v69, v83, s[10:11]
	v_cndmask_b32_e64 v68, v68, v82, s[10:11]
	v_cndmask_b32_e64 v91, v65, v91, s[10:11]
	v_cndmask_b32_e64 v90, v64, v90, s[10:11]
	v_lshl_add_u64 v[64:65], v[74:75], 0, v[226:227]
	v_cvt_pk_bf16_f32 v228, v68, v66
	v_cvt_pk_bf16_f32 v229, v70, v67
	v_cvt_pk_bf16_f32 v230, v90, v91
	v_cvt_pk_bf16_f32 v231, v86, v87
	s_nop 1
	v_permlane16_swap_b32_e32 v228, v230
	v_permlane16_swap_b32_e32 v229, v231
	global_store_dwordx4 v[64:65], v[228:231], off
	s_nop 1

; __device__ __forceinline__ u32x2 pack4(f32x4 v) { u32x2 w; w.x = pk2(v[0], v[1]); w.y = pk2(v[2], v[3]); return w; }
;     __device__ __forceinline__ void operator()(const f32x4 (&acc)[2][2][4][2], const Unit& u, int wr, int wc, int fr, int fq) const {
;     ...
;                     if (cgp < 12) { v0 = v0 * qs; v1 = v1 * qs; }
;                     const int bq = row >> 12, sq = row & (SEQ - 1);
;                     bf16_t* rowp;
;                     if (cgp < 12) rowp = O + ((size_t)(bq * 4 + cgp / 3) * SEQ + sq) * 96 + (cgp % 3) * 32 + 4 * fq;
;                     else if (cgp < 20) rowp = O + (size_t)T * 384 + ((size_t)(bq * 4 + (cgp - 12) / 2) * SEQ + sq) * 64 + ((cgp - 12) & 1) * 32 + 4 * fq;
;                     else rowp = O + (size_t)T * 640 + ((size_t)(bq * 4 + (cgp - 20) / 2) * SEQ + sq) * 64 + ((cgp - 20) & 1) * 32 + 4 * fq;
;                     if (cgp < 28) { *(u32x2*)(rowp) = pack4(v0); *(u32x2*)(rowp + 16) = pack4(v1); }
.LBB0_649:
	v_pk_mul_f32 v[128:129], v[120:121], s[76:77] op_sel_hi:[1,0]
	v_pk_mul_f32 v[148:149], v[118:119], s[76:77] op_sel_hi:[1,0]
	v_pk_mul_f32 v[154:155], v[116:117], s[76:77] op_sel_hi:[1,0]
	v_pk_mul_f32 v[156:157], v[114:115], s[76:77] op_sel_hi:[1,0]
	v_cndmask_b32_e64 v155, v117, v155, s[10:11]
	v_cndmask_b32_e64 v154, v116, v154, s[10:11]
	v_cndmask_b32_e64 v117, v121, v129, s[10:11]
	v_cndmask_b32_e64 v120, v120, v128, s[10:11]
	v_cndmask_b32_e64 v116, v119, v149, s[10:11]
	v_cndmask_b32_e64 v118, v118, v148, s[10:11]
	v_cndmask_b32_e64 v157, v115, v157, s[10:11]
	v_cndmask_b32_e64 v156, v114, v156, s[10:11]
	v_lshl_add_u64 v[114:115], v[124:125], 0, v[226:227]
	v_cvt_pk_bf16_f32 v228, v118, v116
	v_cvt_pk_bf16_f32 v229, v120, v117
	v_cvt_pk_bf16_f32 v230, v156, v157
	v_cvt_pk_bf16_f32 v231, v154, v155
	s_nop 1
	v_permlane16_swap_b32_e32 v228, v230
	v_permlane16_swap_b32_e32 v229, v231
	global_store_dwordx4 v[114:115], v[228:231], off
	s_nop 1
	v_or_b32_e32 v114, 32, v146
	s_and_b64 vcc, exec, s[12:13]
	v_ashrrev_i32_e32 v115, 31, v114
	s_cbranch_vccz .LBB0_561
	s_branch .LBB0_562

; __device__ __forceinline__ u32x2 pack4(f32x4 v) { u32x2 w; w.x = pk2(v[0], v[1]); w.y = pk2(v[2], v[3]); return w; }
;     __device__ __forceinline__ void operator()(const f32x4 (&acc)[2][2][4][2], const Unit& u, int wr, int wc, int fr, int fq) const {
;     ...
;                     if (cgp < 12) { v0 = v0 * qs; v1 = v1 * qs; }
;                     const int bq = row >> 12, sq = row & (SEQ - 1);
;                     bf16_t* rowp;
;                     if (cgp < 12) rowp = O + ((size_t)(bq * 4 + cgp / 3) * SEQ + sq) * 96 + (cgp % 3) * 32 + 4 * fq;
;                     else if (cgp < 20) rowp = O + (size_t)T * 384 + ((size_t)(bq * 4 + (cgp - 12) / 2) * SEQ + sq) * 64 + ((cgp - 12) & 1) * 32 + 4 * fq;
;                     else rowp = O + (size_t)T * 640 + ((size_t)(bq * 4 + (cgp - 20) / 2) * SEQ + sq) * 64 + ((cgp - 20) & 1) * 32 + 4 * fq;
;                     if (cgp < 28) { *(u32x2*)(rowp) = pack4(v0); *(u32x2*)(rowp + 16) = pack4(v1); }
.LBB0_656:
	v_pk_mul_f32 v[120:121], v[110:111], s[76:77] op_sel_hi:[1,0]
	v_pk_mul_f32 v[124:125], v[108:109], s[76:77] op_sel_hi:[1,0]
	v_pk_mul_f32 v[128:129], v[106:107], s[76:77] op_sel_hi:[1,0]
	v_pk_mul_f32 v[148:149], v[104:105], s[76:77] op_sel_hi:[1,0]
	v_cndmask_b32_e64 v129, v107, v129, s[10:11]
	v_cndmask_b32_e64 v128, v106, v128, s[10:11]
	v_cndmask_b32_e64 v107, v111, v121, s[10:11]
	v_cndmask_b32_e64 v110, v110, v120, s[10:11]
	v_cndmask_b32_e64 v106, v109, v125, s[10:11]
	v_cndmask_b32_e64 v108, v108, v124, s[10:11]
	v_cndmask_b32_e64 v149, v105, v149, s[10:11]
	v_cndmask_b32_e64 v148, v104, v148, s[10:11]
	v_lshl_add_u64 v[104:105], v[116:117], 0, v[226:227]
	v_cvt_pk_bf16_f32 v228, v108, v106
	v_cvt_pk_bf16_f32 v229, v110, v107
	v_cvt_pk_bf16_f32 v230, v148, v149
	v_cvt_pk_bf16_f32 v231, v128, v129
	s_nop 1
	v_permlane16_swap_b32_e32 v228, v230
	v_permlane16_swap_b32_e32 v229, v231
	global_store_dwordx4 v[104:105], v[228:231], off
	s_nop 1
	v_or_b32_e32 v104, 48, v146
	s_and_b64 vcc, exec, s[12:13]
	v_ashrrev_i32_e32 v105, 31, v104
	s_cbranch_vccz .LBB0_566
	s_branch .LBB0_567

; __device__ __forceinline__ u32x2 pack4(f32x4 v) { u32x2 w; w.x = pk2(v[0], v[1]); w.y = pk2(v[2], v[3]); return w; }
;     __device__ __forceinline__ void operator()(const f32x4 (&acc)[2][2][4][2], const Unit& u, int wr, int wc, int fr, int fq) const {
;     ...
;                     if (cgp < 12) { v0 = v0 * qs; v1 = v1 * qs; }
;                     const int bq = row >> 12, sq = row & (SEQ - 1);
;                     bf16_t* rowp;
;                     if (cgp < 12) rowp = O + ((size_t)(bq * 4 + cgp / 3) * SEQ + sq) * 96 + (cgp % 3) * 32 + 4 * fq;
;                     else if (cgp < 20) rowp = O + (size_t)T * 384 + ((size_t)(bq * 4 + (cgp - 12) / 2) * SEQ + sq) * 64 + ((cgp - 12) & 1) * 32 + 4 * fq;
;                     else rowp = O + (size_t)T * 640 + ((size_t)(bq * 4 + (cgp - 20) / 2) * SEQ + sq) * 64 + ((cgp - 20) & 1) * 32 + 4 * fq;
;                     if (cgp < 28) { *(u32x2*)(rowp) = pack4(v0); *(u32x2*)(rowp + 16) = pack4(v1); }
.LBB0_663:
	v_pk_mul_f32 v[116:117], v[102:103], s[76:77] op_sel_hi:[1,0]
	v_pk_mul_f32 v[120:121], v[100:101], s[76:77] op_sel_hi:[1,0]
	v_pk_mul_f32 v[124:125], v[98:99], s[76:77] op_sel_hi:[1,0]
	v_pk_mul_f32 v[128:129], v[96:97], s[76:77] op_sel_hi:[1,0]
	v_cndmask_b32_e64 v109, v99, v125, s[10:11]
	v_cndmask_b32_e64 v110, v98, v124, s[10:11]
	v_cndmask_b32_e64 v99, v103, v117, s[10:11]
	v_cndmask_b32_e64 v102, v102, v116, s[10:11]
	v_cndmask_b32_e64 v98, v101, v121, s[10:11]
	v_cndmask_b32_e64 v100, v100, v120, s[10:11]
	v_cndmask_b32_e64 v124, v97, v129, s[10:11]
	v_cndmask_b32_e64 v125, v96, v128, s[10:11]
	v_lshl_add_u64 v[96:97], v[106:107], 0, v[226:227]
	v_cvt_pk_bf16_f32 v228, v100, v98
	v_cvt_pk_bf16_f32 v229, v102, v99
	v_cvt_pk_bf16_f32 v230, v125, v124
	v_cvt_pk_bf16_f32 v231, v110, v109
	s_nop 1
	v_permlane16_swap_b32_e32 v228, v230
	v_permlane16_swap_b32_e32 v229, v231
	global_store_dwordx4 v[96:97], v[228:231], off
	s_nop 1
	v_add_u32_e32 v96, 0x80, v146
	s_and_b64 vcc, exec, s[12:13]
	v_ashrrev_i32_e32 v97, 31, v96
	s_cbranch_vccz .LBB0_571
	s_branch .LBB0_572

; __device__ __forceinline__ u32x2 pack4(f32x4 v) { u32x2 w; w.x = pk2(v[0], v[1]); w.y = pk2(v[2], v[3]); return w; }
;     __device__ __forceinline__ void operator()(const f32x4 (&acc)[2][2][4][2], const Unit& u, int wr, int wc, int fr, int fq) const {
;     ...
;                     if (cgp < 12) { v0 = v0 * qs; v1 = v1 * qs; }
;                     const int bq = row >> 12, sq = row & (SEQ - 1);
;                     bf16_t* rowp;
;                     if (cgp < 12) rowp = O + ((size_t)(bq * 4 + cgp / 3) * SEQ + sq) * 96 + (cgp % 3) * 32 + 4 * fq;
;                     else if (cgp < 20) rowp = O + (size_t)T * 384 + ((size_t)(bq * 4 + (cgp - 12) / 2) * SEQ + sq) * 64 + ((cgp - 12) & 1) * 32 + 4 * fq;
;                     else rowp = O + (size_t)T * 640 + ((size_t)(bq * 4 + (cgp - 20) / 2) * SEQ + sq) * 64 + ((cgp - 20) & 1) * 32 + 4 * fq;
;                     if (cgp < 28) { *(u32x2*)(rowp) = pack4(v0); *(u32x2*)(rowp + 16) = pack4(v1); }
.LBB0_665:
	v_pk_mul_f32 v[120:121], v[94:95], s[76:77] op_sel_hi:[1,0]
	v_pk_mul_f32 v[124:125], v[92:93], s[76:77] op_sel_hi:[1,0]
	v_pk_mul_f32 v[128:129], v[90:91], s[76:77] op_sel_hi:[1,0]
	v_pk_mul_f32 v[148:149], v[88:89], s[76:77] op_sel_hi:[1,0]
	v_cndmask_b32_e64 v117, v91, v129, s[10:11]
	v_cndmask_b32_e64 v128, v90, v128, s[10:11]
	v_cndmask_b32_e64 v91, v95, v121, s[10:11]
	v_cndmask_b32_e64 v94, v94, v120, s[10:11]
	v_cndmask_b32_e64 v90, v93, v125, s[10:11]
	v_cndmask_b32_e64 v92, v92, v124, s[10:11]
	v_cndmask_b32_e64 v129, v89, v149, s[10:11]
	v_cndmask_b32_e64 v148, v88, v148, s[10:11]
	v_lshl_add_u64 v[88:89], v[106:107], 0, v[226:227]
	v_cvt_pk_bf16_f32 v228, v92, v90
	v_cvt_pk_bf16_f32 v229, v94, v91
	v_cvt_pk_bf16_f32 v230, v148, v129
	v_cvt_pk_bf16_f32 v231, v128, v117
	s_nop 1
	v_permlane16_swap_b32_e32 v228, v230
	v_permlane16_swap_b32_e32 v229, v231
	global_store_dwordx4 v[88:89], v[228:231], off
	s_nop 1
	v_add_u32_e32 v88, 0x90, v146
	s_and_b64 vcc, exec, s[12:13]
	v_ashrrev_i32_e32 v89, 31, v88
	s_cbranch_vccz .LBB0_581
	s_branch .LBB0_582

; __device__ __forceinline__ u32x2 pack4(f32x4 v) { u32x2 w; w.x = pk2(v[0], v[1]); w.y = pk2(v[2], v[3]); return w; }
;     __device__ __forceinline__ void operator()(const f32x4 (&acc)[2][2][4][2], const Unit& u, int wr, int wc, int fr, int fq) const {
;     ...
;                     if (cgp < 12) { v0 = v0 * qs; v1 = v1 * qs; }
;                     const int bq = row >> 12, sq = row & (SEQ - 1);
;                     bf16_t* rowp;
;                     if (cgp < 12) rowp = O + ((size_t)(bq * 4 + cgp / 3) * SEQ + sq) * 96 + (cgp % 3) * 32 + 4 * fq;
;                     else if (cgp < 20) rowp = O + (size_t)T * 384 + ((size_t)(bq * 4 + (cgp - 12) / 2) * SEQ + sq) * 64 + ((cgp - 12) & 1) * 32 + 4 * fq;
;                     else rowp = O + (size_t)T * 640 + ((size_t)(bq * 4 + (cgp - 20) / 2) * SEQ + sq) * 64 + ((cgp - 20) & 1) * 32 + 4 * fq;
;                     if (cgp < 28) { *(u32x2*)(rowp) = pack4(v0); *(u32x2*)(rowp + 16) = pack4(v1); }
.LBB0_672:
	v_pk_mul_f32 v[94:95], v[86:87], s[76:77] op_sel_hi:[1,0]
	v_pk_mul_f32 v[106:107], v[84:85], s[76:77] op_sel_hi:[1,0]
	v_pk_mul_f32 v[120:121], v[82:83], s[76:77] op_sel_hi:[1,0]
	v_pk_mul_f32 v[124:125], v[80:81], s[76:77] op_sel_hi:[1,0]
	v_cndmask_b32_e64 v117, v83, v121, s[10:11]
	v_cndmask_b32_e64 v120, v82, v120, s[10:11]
	v_cndmask_b32_e64 v83, v87, v95, s[10:11]
	v_cndmask_b32_e64 v86, v86, v94, s[10:11]
	v_cndmask_b32_e64 v82, v85, v107, s[10:11]
	v_cndmask_b32_e64 v84, v84, v106, s[10:11]
	v_cndmask_b32_e64 v121, v81, v125, s[10:11]
	v_cndmask_b32_e64 v124, v80, v124, s[10:11]
	v_lshl_add_u64 v[80:81], v[90:91], 0, v[226:227]
	v_cvt_pk_bf16_f32 v228, v84, v82
	v_cvt_pk_bf16_f32 v229, v86, v83
	v_cvt_pk_bf16_f32 v230, v124, v121
	v_cvt_pk_bf16_f32 v231, v120, v117
	s_nop 1
	v_permlane16_swap_b32_e32 v228, v230
	v_permlane16_swap_b32_e32 v229, v231
	global_store_dwordx4 v[80:81], v[228:231], off
	s_nop 1
	v_add_u32_e32 v80, 0xa0, v146
	s_and_b64 vcc, exec, s[12:13]
	v_ashrrev_i32_e32 v81, 31, v80
	s_cbranch_vccz .LBB0_586
	s_branch .LBB0_587

; __device__ __forceinline__ u32x2 pack4(f32x4 v) { u32x2 w; w.x = pk2(v[0], v[1]); w.y = pk2(v[2], v[3]); return w; }
;     __device__ __forceinline__ void operator()(const f32x4 (&acc)[2][2][4][2], const Unit& u, int wr, int wc, int fr, int fq) const {
;     ...
;                     if (cgp < 12) { v0 = v0 * qs; v1 = v1 * qs; }
;                     const int bq = row >> 12, sq = row & (SEQ - 1);
;                     bf16_t* rowp;
;                     if (cgp < 12) rowp = O + ((size_t)(bq * 4 + cgp / 3) * SEQ + sq) * 96 + (cgp % 3) * 32 + 4 * fq;
;                     else if (cgp < 20) rowp = O + (size_t)T * 384 + ((size_t)(bq * 4 + (cgp - 12) / 2) * SEQ + sq) * 64 + ((cgp - 12) & 1) * 32 + 4 * fq;
;                     else rowp = O + (size_t)T * 640 + ((size_t)(bq * 4 + (cgp - 20) / 2) * SEQ + sq) * 64 + ((cgp - 20) & 1) * 32 + 4 * fq;
;                     if (cgp < 28) { *(u32x2*)(rowp) = pack4(v0); *(u32x2*)(rowp + 16) = pack4(v1); }
.LBB0_679:
	v_pk_mul_f32 v[86:87], v[78:79], s[76:77] op_sel_hi:[1,0]
	v_pk_mul_f32 v[90:91], v[76:77], s[76:77] op_sel_hi:[1,0]
	v_pk_mul_f32 v[94:95], v[74:75], s[76:77] op_sel_hi:[1,0]
	v_pk_mul_f32 v[106:107], v[72:73], s[76:77] op_sel_hi:[1,0]
	v_cndmask_b32_e64 v95, v75, v95, s[10:11]
	v_cndmask_b32_e64 v94, v74, v94, s[10:11]
	v_cndmask_b32_e64 v75, v79, v87, s[10:11]
	v_cndmask_b32_e64 v78, v78, v86, s[10:11]
	v_cndmask_b32_e64 v74, v77, v91, s[10:11]
	v_cndmask_b32_e64 v76, v76, v90, s[10:11]
	v_cndmask_b32_e64 v107, v73, v107, s[10:11]
	v_cndmask_b32_e64 v106, v72, v106, s[10:11]
	v_lshl_add_u64 v[72:73], v[82:83], 0, v[226:227]
	v_cvt_pk_bf16_f32 v228, v76, v74
	v_cvt_pk_bf16_f32 v229, v78, v75
	v_cvt_pk_bf16_f32 v230, v106, v107
	v_cvt_pk_bf16_f32 v231, v94, v95
	s_nop 1
	v_permlane16_swap_b32_e32 v228, v230
	v_permlane16_swap_b32_e32 v229, v231
	global_store_dwordx4 v[72:73], v[228:231], off
	s_nop 1
	v_add_u32_e32 v72, 0xb0, v146
	s_and_b64 vcc, exec, s[12:13]
	v_ashrrev_i32_e32 v73, 31, v72
	s_cbranch_vccz .LBB0_591
	s_branch .LBB0_592

; __device__ __forceinline__ u32x2 pack4(f32x4 v) { u32x2 w; w.x = pk2(v[0], v[1]); w.y = pk2(v[2], v[3]); return w; }
;     __device__ __forceinline__ void operator()(const f32x4 (&acc)[2][2][4][2], const Unit& u, int wr, int wc, int fr, int fq) const {
;     ...
;                     if (cgp < 12) { v0 = v0 * qs; v1 = v1 * qs; }
;                     const int bq = row >> 12, sq = row & (SEQ - 1);
;                     bf16_t* rowp;
;                     if (cgp < 12) rowp = O + ((size_t)(bq * 4 + cgp / 3) * SEQ + sq) * 96 + (cgp % 3) * 32 + 4 * fq;
;                     else if (cgp < 20) rowp = O + (size_t)T * 384 + ((size_t)(bq * 4 + (cgp - 12) / 2) * SEQ + sq) * 64 + ((cgp - 12) & 1) * 32 + 4 * fq;
;                     else rowp = O + (size_t)T * 640 + ((size_t)(bq * 4 + (cgp - 20) / 2) * SEQ + sq) * 64 + ((cgp - 20) & 1) * 32 + 4 * fq;
;                     if (cgp < 28) { *(u32x2*)(rowp) = pack4(v0); *(u32x2*)(rowp + 16) = pack4(v1); }
.LBB0_689:
	v_pk_mul_f32 v[66:67], v[62:63], s[76:77] op_sel_hi:[1,0]
	v_pk_mul_f32 v[68:69], v[60:61], s[76:77] op_sel_hi:[1,0]
	v_pk_mul_f32 v[70:71], v[58:59], s[76:77] op_sel_hi:[1,0]
	v_pk_mul_f32 v[74:75], v[56:57], s[76:77] op_sel_hi:[1,0]
	v_cndmask_b32_e64 v71, v59, v71, s[10:11]
	v_cndmask_b32_e64 v70, v58, v70, s[10:11]
	v_cndmask_b32_e64 v59, v63, v67, s[10:11]
	v_cndmask_b32_e64 v62, v62, v66, s[10:11]
	v_cndmask_b32_e64 v58, v61, v69, s[10:11]
	v_cndmask_b32_e64 v60, v60, v68, s[10:11]
	v_cndmask_b32_e64 v75, v57, v75, s[10:11]
	v_cndmask_b32_e64 v74, v56, v74, s[10:11]
	v_lshl_add_u64 v[56:57], v[64:65], 0, v[226:227]
	v_cvt_pk_bf16_f32 v228, v60, v58
	v_cvt_pk_bf16_f32 v229, v62, v59
	v_cvt_pk_bf16_f32 v230, v74, v75
	v_cvt_pk_bf16_f32 v231, v70, v71
	s_nop 1
	v_permlane16_swap_b32_e32 v228, v230
	v_permlane16_swap_b32_e32 v229, v231
	global_store_dwordx4 v[56:57], v[228:231], off
	s_nop 1
	s_and_b64 vcc, exec, s[12:13]
	s_cbranch_vccnz .LBB0_609

; __device__ __forceinline__ u32x2 pack4(f32x4 v) { u32x2 w; w.x = pk2(v[0], v[1]); w.y = pk2(v[2], v[3]); return w; }
;     __device__ __forceinline__ void operator()(const f32x4 (&acc)[2][2][4][2], const Unit& u, int wr, int wc, int fr, int fq) const {
;     ...
;                 for (int m = 0; m < 4; ++m) {
;                     const int row = row0 + ai * HALF + m * 16;
;                     f32x4 v0 = acc[ai][bj][m][0], v1 = acc[ai][bj][m][1];
;                     if (rope) {
;                         const f32x4 c = *(const f32x4*)(cs + (size_t)row * 32 + 4 * fq), s = *(const f32x4*)(cs + (size_t)row * 32 + 16 + 4 * fq);
;                         const f32x4 a = v0 * c - v1 * s, b = v1 * c + v0 * s; v0 = a; v1 = b;
;                     }
;                     if (cgp < 12) { v0 = v0 * qs; v1 = v1 * qs; }
;                     const int bq = row >> 12, sq = row & (SEQ - 1);
;                     bf16_t* rowp;
;                     if (cgp < 12) rowp = O + ((size_t)(bq * 4 + cgp / 3) * SEQ + sq) * 96 + (cgp % 3) * 32 + 4 * fq;
;                     else if (cgp < 20) rowp = O + (size_t)T * 384 + ((size_t)(bq * 4 + (cgp - 12) / 2) * SEQ + sq) * 64 + ((cgp - 12) & 1) * 32 + 4 * fq;
;                     else rowp = O + (size_t)T * 640 + ((size_t)(bq * 4 + (cgp - 20) / 2) * SEQ + sq) * 64 + ((cgp - 20) & 1) * 32 + 4 * fq;
;                     if (cgp < 28) { *(u32x2*)(rowp) = pack4(v0); *(u32x2*)(rowp + 16) = pack4(v1); }
.LBB0_697:
	v_pk_mul_f32 v[58:59], v[54:55], s[76:77] op_sel_hi:[1,0]
	v_pk_mul_f32 v[60:61], v[52:53], s[76:77] op_sel_hi:[1,0]
	v_pk_mul_f32 v[62:63], v[50:51], s[76:77] op_sel_hi:[1,0]
	v_pk_mul_f32 v[64:65], v[48:49], s[76:77] op_sel_hi:[1,0]
	v_cndmask_b32_e64 v63, v51, v63, s[10:11]
	v_cndmask_b32_e64 v62, v50, v62, s[10:11]
	v_cndmask_b32_e64 v51, v55, v59, s[10:11]
	v_cndmask_b32_e64 v54, v54, v58, s[10:11]
	v_cndmask_b32_e64 v50, v53, v61, s[10:11]
	v_cndmask_b32_e64 v52, v52, v60, s[10:11]
	v_cndmask_b32_e64 v65, v49, v65, s[10:11]
	v_cndmask_b32_e64 v64, v48, v64, s[10:11]
	v_lshl_add_u64 v[48:49], v[56:57], 0, v[226:227]
	v_cvt_pk_bf16_f32 v228, v52, v50
	v_cvt_pk_bf16_f32 v229, v54, v51
	v_cvt_pk_bf16_f32 v230, v64, v65
	v_cvt_pk_bf16_f32 v231, v62, v63
	s_nop 1
	v_permlane16_swap_b32_e32 v228, v230
	v_permlane16_swap_b32_e32 v229, v231
	global_store_dwordx4 v[48:49], v[228:231], off
	s_nop 1
	s_and_b64 vcc, exec, s[12:13]
	s_cbranch_vccnz .LBB0_613

; __device__ __forceinline__ u32x2 pack4(f32x4 v) { u32x2 w; w.x = pk2(v[0], v[1]); w.y = pk2(v[2], v[3]); return w; }
;     __device__ __forceinline__ void operator()(const f32x4 (&acc)[2][2][4][2], const Unit& u, int wr, int wc, int fr, int fq) const {
;     ...
;                 for (int m = 0; m < 4; ++m) {
;                     const int row = row0 + ai * HALF + m * 16;
;                     f32x4 v0 = acc[ai][bj][m][0], v1 = acc[ai][bj][m][1];
;                     if (rope) {
;                         const f32x4 c = *(const f32x4*)(cs + (size_t)row * 32 + 4 * fq), s = *(const f32x4*)(cs + (size_t)row * 32 + 16 + 4 * fq);
;                         const f32x4 a = v0 * c - v1 * s, b = v1 * c + v0 * s; v0 = a; v1 = b;
;                     }
;                     if (cgp < 12) { v0 = v0 * qs; v1 = v1 * qs; }
;                     const int bq = row >> 12, sq = row & (SEQ - 1);
;                     bf16_t* rowp;
;                     if (cgp < 12) rowp = O + ((size_t)(bq * 4 + cgp / 3) * SEQ + sq) * 96 + (cgp % 3) * 32 + 4 * fq;
;                     else if (cgp < 20) rowp = O + (size_t)T * 384 + ((size_t)(bq * 4 + (cgp - 12) / 2) * SEQ + sq) * 64 + ((cgp - 12) & 1) * 32 + 4 * fq;
;                     else rowp = O + (size_t)T * 640 + ((size_t)(bq * 4 + (cgp - 20) / 2) * SEQ + sq) * 64 + ((cgp - 20) & 1) * 32 + 4 * fq;
;                     if (cgp < 28) { *(u32x2*)(rowp) = pack4(v0); *(u32x2*)(rowp + 16) = pack4(v1); }
.LBB0_705:
	v_pk_mul_f32 v[50:51], v[46:47], s[76:77] op_sel_hi:[1,0]
	v_pk_mul_f32 v[52:53], v[44:45], s[76:77] op_sel_hi:[1,0]
	v_pk_mul_f32 v[54:55], v[42:43], s[76:77] op_sel_hi:[1,0]
	v_pk_mul_f32 v[56:57], v[40:41], s[76:77] op_sel_hi:[1,0]
	v_cndmask_b32_e64 v55, v43, v55, s[10:11]
	v_cndmask_b32_e64 v54, v42, v54, s[10:11]
	v_cndmask_b32_e64 v43, v47, v51, s[10:11]
	v_cndmask_b32_e64 v46, v46, v50, s[10:11]
	v_cndmask_b32_e64 v42, v45, v53, s[10:11]
	v_cndmask_b32_e64 v44, v44, v52, s[10:11]
	v_cndmask_b32_e64 v57, v41, v57, s[10:11]
	v_cndmask_b32_e64 v56, v40, v56, s[10:11]
	v_lshl_add_u64 v[40:41], v[48:49], 0, v[226:227]
	v_cvt_pk_bf16_f32 v228, v44, v42
	v_cvt_pk_bf16_f32 v229, v46, v43
	v_cvt_pk_bf16_f32 v230, v56, v57
	v_cvt_pk_bf16_f32 v231, v54, v55
	s_nop 1
	v_permlane16_swap_b32_e32 v228, v230
	v_permlane16_swap_b32_e32 v229, v231
	global_store_dwordx4 v[40:41], v[228:231], off
	s_nop 1
	s_and_b64 vcc, exec, s[12:13]
	s_cbranch_vccnz .LBB0_617

; __device__ __forceinline__ u32x2 pack4(f32x4 v) { u32x2 w; w.x = pk2(v[0], v[1]); w.y = pk2(v[2], v[3]); return w; }
;     __device__ __forceinline__ void operator()(const f32x4 (&acc)[2][2][4][2], const Unit& u, int wr, int wc, int fr, int fq) const {
;     ...
;                 for (int m = 0; m < 4; ++m) {
;                     const int row = row0 + ai * HALF + m * 16;
;                     f32x4 v0 = acc[ai][bj][m][0], v1 = acc[ai][bj][m][1];
;                     if (rope) {
;                         const f32x4 c = *(const f32x4*)(cs + (size_t)row * 32 + 4 * fq), s = *(const f32x4*)(cs + (size_t)row * 32 + 16 + 4 * fq);
;                         const f32x4 a = v0 * c - v1 * s, b = v1 * c + v0 * s; v0 = a; v1 = b;
;                     }
;                     if (cgp < 12) { v0 = v0 * qs; v1 = v1 * qs; }
;                     const int bq = row >> 12, sq = row & (SEQ - 1);
;                     bf16_t* rowp;
;                     if (cgp < 12) rowp = O + ((size_t)(bq * 4 + cgp / 3) * SEQ + sq) * 96 + (cgp % 3) * 32 + 4 * fq;
;                     else if (cgp < 20) rowp = O + (size_t)T * 384 + ((size_t)(bq * 4 + (cgp - 12) / 2) * SEQ + sq) * 64 + ((cgp - 12) & 1) * 32 + 4 * fq;
;                     else rowp = O + (size_t)T * 640 + ((size_t)(bq * 4 + (cgp - 20) / 2) * SEQ + sq) * 64 + ((cgp - 20) & 1) * 32 + 4 * fq;
;                     if (cgp < 28) { *(u32x2*)(rowp) = pack4(v0); *(u32x2*)(rowp + 16) = pack4(v1); }
.LBB0_713:
	v_pk_mul_f32 v[42:43], v[38:39], s[76:77] op_sel_hi:[1,0]
	v_pk_mul_f32 v[44:45], v[36:37], s[76:77] op_sel_hi:[1,0]
	v_pk_mul_f32 v[46:47], v[34:35], s[76:77] op_sel_hi:[1,0]
	v_pk_mul_f32 v[48:49], v[32:33], s[76:77] op_sel_hi:[1,0]
	v_cndmask_b32_e64 v47, v35, v47, s[10:11]
	v_cndmask_b32_e64 v46, v34, v46, s[10:11]
	v_cndmask_b32_e64 v35, v39, v43, s[10:11]
	v_cndmask_b32_e64 v38, v38, v42, s[10:11]
	v_cndmask_b32_e64 v34, v37, v45, s[10:11]
	v_cndmask_b32_e64 v36, v36, v44, s[10:11]
	v_cndmask_b32_e64 v49, v33, v49, s[10:11]
	v_cndmask_b32_e64 v48, v32, v48, s[10:11]
	v_lshl_add_u64 v[32:33], v[40:41], 0, v[226:227]
	v_cvt_pk_bf16_f32 v228, v36, v34
	v_cvt_pk_bf16_f32 v229, v38, v35
	v_cvt_pk_bf16_f32 v230, v48, v49
	v_cvt_pk_bf16_f32 v231, v46, v47
	s_nop 1
	v_permlane16_swap_b32_e32 v228, v230
	v_permlane16_swap_b32_e32 v229, v231
	global_store_dwordx4 v[32:33], v[228:231], off
	s_nop 1
	s_and_b64 vcc, exec, s[12:13]
	s_cbranch_vccz .LBB0_621
	s_branch .LBB0_622

; __device__ __forceinline__ u32x2 pack4(f32x4 v) { u32x2 w; w.x = pk2(v[0], v[1]); w.y = pk2(v[2], v[3]); return w; }
;     __device__ __forceinline__ void operator()(const f32x4 (&acc)[2][2][4][2], const Unit& u, int wr, int wc, int fr, int fq) const {
;     ...
;                 for (int m = 0; m < 4; ++m) {
;                     const int row = row0 + ai * HALF + m * 16;
;                     f32x4 v0 = acc[ai][bj][m][0], v1 = acc[ai][bj][m][1];
;                     if (rope) {
;                         const f32x4 c = *(const f32x4*)(cs + (size_t)row * 32 + 4 * fq), s = *(const f32x4*)(cs + (size_t)row * 32 + 16 + 4 * fq);
;                         const f32x4 a = v0 * c - v1 * s, b = v1 * c + v0 * s; v0 = a; v1 = b;
;                     }
;                     if (cgp < 12) { v0 = v0 * qs; v1 = v1 * qs; }
;                     const int bq = row >> 12, sq = row & (SEQ - 1);
;                     bf16_t* rowp;
;                     if (cgp < 12) rowp = O + ((size_t)(bq * 4 + cgp / 3) * SEQ + sq) * 96 + (cgp % 3) * 32 + 4 * fq;
;                     else if (cgp < 20) rowp = O + (size_t)T * 384 + ((size_t)(bq * 4 + (cgp - 12) / 2) * SEQ + sq) * 64 + ((cgp - 12) & 1) * 32 + 4 * fq;
;                     else rowp = O + (size_t)T * 640 + ((size_t)(bq * 4 + (cgp - 20) / 2) * SEQ + sq) * 64 + ((cgp - 20) & 1) * 32 + 4 * fq;
;                     if (cgp < 28) { *(u32x2*)(rowp) = pack4(v0); *(u32x2*)(rowp + 16) = pack4(v1); }
.LBB0_715:
	v_pk_mul_f32 v[40:41], v[30:31], s[76:77] op_sel_hi:[1,0]
	v_pk_mul_f32 v[42:43], v[28:29], s[76:77] op_sel_hi:[1,0]
	v_pk_mul_f32 v[44:45], v[26:27], s[76:77] op_sel_hi:[1,0]
	v_pk_mul_f32 v[46:47], v[24:25], s[76:77] op_sel_hi:[1,0]
	v_cndmask_b32_e64 v45, v27, v45, s[10:11]
	v_cndmask_b32_e64 v44, v26, v44, s[10:11]
	v_cndmask_b32_e64 v27, v31, v41, s[10:11]
	v_cndmask_b32_e64 v30, v30, v40, s[10:11]
	v_cndmask_b32_e64 v26, v29, v43, s[10:11]
	v_cndmask_b32_e64 v28, v28, v42, s[10:11]
	v_cndmask_b32_e64 v47, v25, v47, s[10:11]
	v_cndmask_b32_e64 v46, v24, v46, s[10:11]
	v_lshl_add_u64 v[24:25], v[38:39], 0, v[226:227]
	v_cvt_pk_bf16_f32 v228, v28, v26
	v_cvt_pk_bf16_f32 v229, v30, v27
	v_cvt_pk_bf16_f32 v230, v46, v47
	v_cvt_pk_bf16_f32 v231, v44, v45
	s_nop 1
	v_permlane16_swap_b32_e32 v228, v230
	v_permlane16_swap_b32_e32 v229, v231
	global_store_dwordx4 v[24:25], v[228:231], off
	s_nop 1
	s_and_b64 vcc, exec, s[12:13]
	s_cbranch_vccnz .LBB0_631

; __device__ __forceinline__ u32x2 pack4(f32x4 v) { u32x2 w; w.x = pk2(v[0], v[1]); w.y = pk2(v[2], v[3]); return w; }
;     __device__ __forceinline__ void operator()(const f32x4 (&acc)[2][2][4][2], const Unit& u, int wr, int wc, int fr, int fq) const {
;     ...
;                 for (int m = 0; m < 4; ++m) {
;                     const int row = row0 + ai * HALF + m * 16;
;                     f32x4 v0 = acc[ai][bj][m][0], v1 = acc[ai][bj][m][1];
;                     if (rope) {
;                         const f32x4 c = *(const f32x4*)(cs + (size_t)row * 32 + 4 * fq), s = *(const f32x4*)(cs + (size_t)row * 32 + 16 + 4 * fq);
;                         const f32x4 a = v0 * c - v1 * s, b = v1 * c + v0 * s; v0 = a; v1 = b;
;                     }
;                     if (cgp < 12) { v0 = v0 * qs; v1 = v1 * qs; }
;                     const int bq = row >> 12, sq = row & (SEQ - 1);
;                     bf16_t* rowp;
;                     if (cgp < 12) rowp = O + ((size_t)(bq * 4 + cgp / 3) * SEQ + sq) * 96 + (cgp % 3) * 32 + 4 * fq;
;                     else if (cgp < 20) rowp = O + (size_t)T * 384 + ((size_t)(bq * 4 + (cgp - 12) / 2) * SEQ + sq) * 64 + ((cgp - 12) & 1) * 32 + 4 * fq;
;                     else rowp = O + (size_t)T * 640 + ((size_t)(bq * 4 + (cgp - 20) / 2) * SEQ + sq) * 64 + ((cgp - 20) & 1) * 32 + 4 * fq;
;                     if (cgp < 28) { *(u32x2*)(rowp) = pack4(v0); *(u32x2*)(rowp + 16) = pack4(v1); }
.LBB0_723:
	v_pk_mul_f32 v[26:27], v[22:23], s[76:77] op_sel_hi:[1,0]
	v_pk_mul_f32 v[28:29], v[20:21], s[76:77] op_sel_hi:[1,0]
	v_pk_mul_f32 v[30:31], v[18:19], s[76:77] op_sel_hi:[1,0]
	v_pk_mul_f32 v[38:39], v[16:17], s[76:77] op_sel_hi:[1,0]
	v_cndmask_b32_e64 v31, v19, v31, s[10:11]
	v_cndmask_b32_e64 v30, v18, v30, s[10:11]
	v_cndmask_b32_e64 v19, v23, v27, s[10:11]
	v_cndmask_b32_e64 v22, v22, v26, s[10:11]
	v_cndmask_b32_e64 v18, v21, v29, s[10:11]
	v_cndmask_b32_e64 v20, v20, v28, s[10:11]
	v_cndmask_b32_e64 v39, v17, v39, s[10:11]
	v_cndmask_b32_e64 v38, v16, v38, s[10:11]
	v_lshl_add_u64 v[16:17], v[24:25], 0, v[226:227]
	v_cvt_pk_bf16_f32 v228, v20, v18
	v_cvt_pk_bf16_f32 v229, v22, v19
	v_cvt_pk_bf16_f32 v230, v38, v39
	v_cvt_pk_bf16_f32 v231, v30, v31
	s_nop 1
	v_permlane16_swap_b32_e32 v228, v230
	v_permlane16_swap_b32_e32 v229, v231
	global_store_dwordx4 v[16:17], v[228:231], off
	s_nop 1
	s_and_b64 vcc, exec, s[12:13]
	s_cbranch_vccnz .LBB0_635

; __device__ __forceinline__ u32x2 pack4(f32x4 v) { u32x2 w; w.x = pk2(v[0], v[1]); w.y = pk2(v[2], v[3]); return w; }
;     __device__ __forceinline__ void operator()(const f32x4 (&acc)[2][2][4][2], const Unit& u, int wr, int wc, int fr, int fq) const {
;     ...
;                 for (int m = 0; m < 4; ++m) {
;                     const int row = row0 + ai * HALF + m * 16;
;                     f32x4 v0 = acc[ai][bj][m][0], v1 = acc[ai][bj][m][1];
;                     if (rope) {
;                         const f32x4 c = *(const f32x4*)(cs + (size_t)row * 32 + 4 * fq), s = *(const f32x4*)(cs + (size_t)row * 32 + 16 + 4 * fq);
;                         const f32x4 a = v0 * c - v1 * s, b = v1 * c + v0 * s; v0 = a; v1 = b;
;                     }
;                     if (cgp < 12) { v0 = v0 * qs; v1 = v1 * qs; }
;                     const int bq = row >> 12, sq = row & (SEQ - 1);
;                     bf16_t* rowp;
;                     if (cgp < 12) rowp = O + ((size_t)(bq * 4 + cgp / 3) * SEQ + sq) * 96 + (cgp % 3) * 32 + 4 * fq;
;                     else if (cgp < 20) rowp = O + (size_t)T * 384 + ((size_t)(bq * 4 + (cgp - 12) / 2) * SEQ + sq) * 64 + ((cgp - 12) & 1) * 32 + 4 * fq;
;                     else rowp = O + (size_t)T * 640 + ((size_t)(bq * 4 + (cgp - 20) / 2) * SEQ + sq) * 64 + ((cgp - 20) & 1) * 32 + 4 * fq;
;                     if (cgp < 28) { *(u32x2*)(rowp) = pack4(v0); *(u32x2*)(rowp + 16) = pack4(v1); }
.LBB0_731:
	v_pk_mul_f32 v[18:19], v[14:15], s[76:77] op_sel_hi:[1,0]
	v_pk_mul_f32 v[20:21], v[12:13], s[76:77] op_sel_hi:[1,0]
	v_pk_mul_f32 v[22:23], v[10:11], s[76:77] op_sel_hi:[1,0]
	v_pk_mul_f32 v[24:25], v[8:9], s[76:77] op_sel_hi:[1,0]
	v_cndmask_b32_e64 v23, v11, v23, s[10:11]
	v_cndmask_b32_e64 v22, v10, v22, s[10:11]
	v_cndmask_b32_e64 v11, v15, v19, s[10:11]
	v_cndmask_b32_e64 v14, v14, v18, s[10:11]
	v_cndmask_b32_e64 v10, v13, v21, s[10:11]
	v_cndmask_b32_e64 v12, v12, v20, s[10:11]
	v_cndmask_b32_e64 v25, v9, v25, s[10:11]
	v_cndmask_b32_e64 v24, v8, v24, s[10:11]
	v_lshl_add_u64 v[8:9], v[16:17], 0, v[226:227]
	v_cvt_pk_bf16_f32 v228, v12, v10
	v_cvt_pk_bf16_f32 v229, v14, v11
	v_cvt_pk_bf16_f32 v230, v24, v25
	v_cvt_pk_bf16_f32 v231, v22, v23
	s_nop 1
	v_permlane16_swap_b32_e32 v228, v230
	v_permlane16_swap_b32_e32 v229, v231
	global_store_dwordx4 v[8:9], v[228:231], off
	s_nop 1
	s_and_b64 vcc, exec, s[12:13]
	s_cbranch_vccnz .LBB0_639

; __device__ __forceinline__ u32x2 pack4(f32x4 v) { u32x2 w; w.x = pk2(v[0], v[1]); w.y = pk2(v[2], v[3]); return w; }
;     __device__ __forceinline__ void operator()(const f32x4 (&acc)[2][2][4][2], const Unit& u, int wr, int wc, int fr, int fq) const {
;     ...
;                 for (int m = 0; m < 4; ++m) {
;                     const int row = row0 + ai * HALF + m * 16;
;                     f32x4 v0 = acc[ai][bj][m][0], v1 = acc[ai][bj][m][1];
;                     if (rope) {
;                         const f32x4 c = *(const f32x4*)(cs + (size_t)row * 32 + 4 * fq), s = *(const f32x4*)(cs + (size_t)row * 32 + 16 + 4 * fq);
;                         const f32x4 a = v0 * c - v1 * s, b = v1 * c + v0 * s; v0 = a; v1 = b;
;                     }
;                     if (cgp < 12) { v0 = v0 * qs; v1 = v1 * qs; }
;                     const int bq = row >> 12, sq = row & (SEQ - 1);
;                     bf16_t* rowp;
;                     if (cgp < 12) rowp = O + ((size_t)(bq * 4 + cgp / 3) * SEQ + sq) * 96 + (cgp % 3) * 32 + 4 * fq;
;                     else if (cgp < 20) rowp = O + (size_t)T * 384 + ((size_t)(bq * 4 + (cgp - 12) / 2) * SEQ + sq) * 64 + ((cgp - 12) & 1) * 32 + 4 * fq;
;                     else rowp = O + (size_t)T * 640 + ((size_t)(bq * 4 + (cgp - 20) / 2) * SEQ + sq) * 64 + ((cgp - 20) & 1) * 32 + 4 * fq;
;                     if (cgp < 28) { *(u32x2*)(rowp) = pack4(v0); *(u32x2*)(rowp + 16) = pack4(v1); }
.LBB0_739:
	v_pk_mul_f32 v[10:11], v[6:7], s[76:77] op_sel_hi:[1,0]
	v_pk_mul_f32 v[12:13], v[4:5], s[76:77] op_sel_hi:[1,0]
	v_pk_mul_f32 v[14:15], v[2:3], s[76:77] op_sel_hi:[1,0]
	v_pk_mul_f32 v[16:17], v[0:1], s[76:77] op_sel_hi:[1,0]
	v_cndmask_b32_e64 v15, v3, v15, s[10:11]
	v_cndmask_b32_e64 v14, v2, v14, s[10:11]
	v_cndmask_b32_e64 v3, v7, v11, s[10:11]
	v_cndmask_b32_e64 v6, v6, v10, s[10:11]
	v_cndmask_b32_e64 v2, v5, v13, s[10:11]
	v_cndmask_b32_e64 v4, v4, v12, s[10:11]
	v_cndmask_b32_e64 v17, v1, v17, s[10:11]
	v_cndmask_b32_e64 v16, v0, v16, s[10:11]
	v_lshl_add_u64 v[0:1], v[8:9], 0, v[226:227]
	v_cvt_pk_bf16_f32 v228, v4, v2
	v_cvt_pk_bf16_f32 v229, v6, v3
	v_cvt_pk_bf16_f32 v230, v16, v17
	v_cvt_pk_bf16_f32 v231, v14, v15
	s_nop 1
	v_permlane16_swap_b32_e32 v228, v230
	v_permlane16_swap_b32_e32 v229, v231
	global_store_dwordx4 v[0:1], v[228:231], off
	s_nop 1
	s_and_b64 vcc, exec, s[8:9]
	s_mov_b64 s[4:5], -1
	s_cbranch_vccnz .LBB0_524
